# k28 + static s_setprio 1 for waves 0-3 during the P6 mixer phases (reset to 0 at P6 exit)
# speedup vs baseline: 1.0097x; 1.0097x over previous
; __device__ __forceinline__ float wave_max(float v) {
; #pragma unroll
;     for (int o = 1; o < 64; o <<= 1) v = fmaxf(v, __shfl_xor(v, o));
;     return v;
; }
; __global__ void __launch_bounds__(NWAVES * 64, 2) fwd_megakernel(Args args) {
;     ...
;     {
;         bf16_t* OACC = (bf16_t*)(ws + WS_ORAW); float* LACC = (float*)ws;
;         bf16_t* SLOC = (bf16_t*)(ws + WS_SLOC); float* DG = (float*)(ws + WS_DG);
;         const float* gq = args.in[8]; const float* gk = args.in[9];
;         const float mq = wave_max(fmaxf(fabsf(gq[2 * F.lane]), fabsf(gq[2 * F.lane + 1]))), mk = wave_max(fmaxf(fabsf(gk[2 * F.lane]), fabsf(gk[2 * F.lane + 1])));
;         const float nb2 = -11.313708499f * mq * mk * 1.44269504089f;
;         for (int it = blockIdx.x; it < 256; it += F.G) gla_item<0>(F, it >> 6, it & 63, BB, BZ, args.in[10], args.in[11], args.in[12], SLOC, DG, H);
.LBB0_458:
	s_or_b64 exec, exec, s[0:1]
	s_cmp_lt_u32 s65, 4
	s_cbranch_scc0 .Lp6_prio_skip
	s_setprio 1
.Lp6_prio_skip:
	s_waitcnt lgkmcnt(0)
	s_barrier
	global_load_dwordx2 v[0:1], v140, s[36:37]
	global_load_dwordx2 v[2:3], v140, s[38:39]
	v_mbcnt_hi_u32_b32 v4, -1, v166
	v_and_b32_e32 v5, 64, v4
	v_xor_b32_e32 v6, 1, v4
	v_add_u32_e32 v5, 64, v5
	v_cmp_lt_i32_e32 vcc, v6, v5
	v_xor_b32_e32 v7, 2, v4
	v_xor_b32_e32 v8, 4, v4
	v_cndmask_b32_e32 v6, v4, v6, vcc
	v_lshlrev_b32_e32 v137, 2, v6
	v_cmp_lt_i32_e32 vcc, v7, v5
	v_xor_b32_e32 v9, 8, v4
	v_xor_b32_e32 v10, 16, v4
	v_cndmask_b32_e32 v6, v4, v7, vcc
	v_lshlrev_b32_e32 v203, 2, v6
	v_cmp_lt_i32_e32 vcc, v8, v5
	v_xor_b32_e32 v11, 32, v4
	s_add_u32 s36, s62, 0x11c00000
	v_cndmask_b32_e32 v6, v4, v8, vcc
	v_lshlrev_b32_e32 v204, 2, v6
	v_cmp_lt_i32_e32 vcc, v9, v5
	s_addc_u32 s37, s63, 0
	s_cmpk_lt_i32 s2, 0x100
	v_cndmask_b32_e32 v6, v4, v9, vcc
	v_lshlrev_b32_e32 v205, 2, v6
	v_cmp_lt_i32_e32 vcc, v10, v5
	s_mov_b32 s13, 0
	s_movk_i32 s0, 0x100
	v_cndmask_b32_e32 v6, v4, v10, vcc
	v_lshlrev_b32_e32 v206, 2, v6
	v_cmp_lt_i32_e32 vcc, v11, v5
	s_movk_i32 s6, 0xff
	s_cselect_b64 s[18:19], -1, 0
	v_cndmask_b32_e32 v4, v4, v11, vcc
	v_lshlrev_b32_e32 v207, 2, v4
	s_cmpk_gt_i32 s2, 0xff
	v_lshrrev_b32_e32 v133, 4, v202
	v_lshlrev_b32_e32 v134, 4, v136
	v_lshrrev_b32_e32 v143, 5, v136
	v_lshrrev_b32_e32 v141, 4, v136
	s_waitcnt vmcnt(1)
	v_max_f32_e64 v1, |v1|, |v1|
	v_max_f32_e64 v0, |v0|, |v0|
	s_waitcnt vmcnt(0)
	v_max_f32_e64 v3, |v3|, |v3|
	v_max_f32_e64 v2, |v2|, |v2|
	v_max_f32_e32 v0, v0, v1
	v_max_f32_e32 v1, v2, v3
	ds_bpermute_b32 v2, v137, v0
	ds_bpermute_b32 v3, v137, v1
	s_waitcnt lgkmcnt(1)
	v_max_f32_e32 v2, v2, v2
	s_waitcnt lgkmcnt(0)
	v_max_f32_e32 v3, v3, v3
	v_max_f32_e32 v0, v0, v2
	v_max_f32_e32 v1, v1, v3
	ds_bpermute_b32 v2, v203, v0
	ds_bpermute_b32 v3, v203, v1
	s_waitcnt lgkmcnt(1)
	v_max_f32_e32 v2, v2, v2
	s_waitcnt lgkmcnt(0)
	v_max_f32_e32 v3, v3, v3
	v_max_f32_e32 v0, v0, v2
	v_max_f32_e32 v1, v1, v3
	ds_bpermute_b32 v2, v204, v0
	ds_bpermute_b32 v3, v204, v1
	s_waitcnt lgkmcnt(1)
	v_max_f32_e32 v2, v2, v2
	s_waitcnt lgkmcnt(0)
	v_max_f32_e32 v3, v3, v3
	v_max_f32_e32 v0, v0, v2
	v_max_f32_e32 v1, v1, v3
	ds_bpermute_b32 v2, v205, v0
	ds_bpermute_b32 v3, v205, v1
	s_waitcnt lgkmcnt(1)
	v_max_f32_e32 v2, v2, v2
	s_waitcnt lgkmcnt(0)
	v_max_f32_e32 v3, v3, v3
	v_max_f32_e32 v0, v0, v2
	v_max_f32_e32 v1, v1, v3
	ds_bpermute_b32 v2, v206, v0
	ds_bpermute_b32 v3, v206, v1
	s_waitcnt lgkmcnt(1)
	v_max_f32_e32 v2, v2, v2
	s_waitcnt lgkmcnt(0)
	v_max_f32_e32 v3, v3, v3
	v_max_f32_e32 v103, v0, v2
	v_max_f32_e32 v102, v1, v3
	ds_bpermute_b32 v105, v207, v103
	ds_bpermute_b32 v104, v207, v102
	s_cbranch_scc1 .LBB0_473
	v_add_u32_e32 v1, 0x200, v136
	v_mov_b32_e32 v81, 0
	v_lshrrev_b32_e32 v110, 5, v1
	v_lshrrev_b32_e32 v113, 4, v1
	s_movk_i32 s25, 0x220
	v_mov_b32_e32 v1, 0x4400
	v_and_b32_e32 v0, 0xf0, v134
	v_mad_u32_u24 v7, v143, s25, v1
	v_mov_b32_e32 v1, v81
	s_add_u32 s14, s62, 0x6400000
	v_and_b32_e32 v106, 0x7f, v136
	v_add_u32_e32 v3, 0, v0
	v_readlane_b32 s7, v254, 13
	v_add_u32_e32 v5, 0x600, v136
	v_lshl_add_u64 v[86:87], s[36:37], 0, v[0:1]
	v_lshrrev_b32_e32 v0, 7, v136
	s_addc_u32 s15, s63, 0
	v_and_b32_e32 v80, 0x1f0, v134
	s_add_i32 s4, 0, 0x18c00
	v_lshlrev_b32_e32 v4, 2, v106
	s_andn2_b32 s7, s7, 63
	v_lshrrev_b32_e32 v112, 5, v5
	v_mul_u32_u24_e32 v1, 0x1200, v0
	v_add_u32_e32 v2, 0, v80
	v_lshl_add_u32 v107, v136, 2, s4
	v_add_u32_e32 v108, s4, v4
	s_movk_i32 s4, 0x80
	s_add_i32 s24, s7, 0
	v_mov_b32_e32 v135, v81
	s_add_i32 s7, 0, 0x19400
	v_mul_u32_u24_e32 v5, 0x220, v143
	v_mul_u32_u24_e32 v6, 0x220, v110
	v_mul_u32_u24_e32 v8, 0x220, v112
	v_mul_u32_u24_e32 v9, 0x120, v141
	v_mul_u32_u24_e32 v10, 0x120, v113
	s_movk_i32 s8, 0x17f
	s_movk_i32 s10, 0x1ff
	v_lshl_add_u64 v[84:85], s[36:37], 0, v[80:81]
	v_lshl_or_b32 v1, v106, 1, v1
	v_lshl_or_b32 v80, v0, 16, v4
	v_cmp_gt_u32_e64 s[0:1], s0, v136
	v_cmp_gt_u32_e64 s[4:5], s4, v136
	v_lshl_add_u64 v[82:83], s[34:35], 0, v[134:135]
	v_add_u32_e32 v109, s7, v4
	v_or_b32_e32 v111, 32, v143
	s_movk_i32 s26, 0x120
	v_cmp_lt_u32_e64 s[6:7], s6, v136
	v_cmp_lt_u32_e64 s[8:9], s8, v136
	v_cmp_lt_u32_e64 s[10:11], s10, v136
	s_lshl_b32 s27, s65, 8
	v_lshl_or_b32 v114, v0, 13, v4
	v_lshlrev_b32_e32 v115, 10, v0
	v_add_u32_e32 v116, 0x8800, v1
	v_lshl_add_u64 v[88:89], s[62:63], 0, v[80:81]
	s_lshl_b32 s28, s2, 8
	s_lshl_b32 s29, s30, 8
	s_movk_i32 s38, 0x1800
	v_add_u32_e32 v117, v2, v5
	v_add_u32_e32 v118, v2, v6
	v_add_u32_e32 v119, v2, v7
	v_add_u32_e32 v120, v2, v8
	v_add_u32_e32 v121, v3, v9
	v_add_u32_e32 v122, v3, v10
	s_mov_b32 s39, 0x800000
	s_mov_b32 s50, 0x3f317217
	s_mov_b32 s51, 0x7f800000
	s_mov_b32 s71, 0x7c01000
	s_mov_b64 s[16:17], 0x40000
	v_mov_b32_e32 v123, 0x41b17218
	s_mov_b32 s20, s2
	s_branch .LBB0_461

; __device__ __forceinline__ unsigned xb_ld(unsigned* p)              { return __hip_atomic_load(p, __ATOMIC_RELAXED, __HIP_MEMORY_SCOPE_AGENT); }
; __device__ __forceinline__ void xcd_barrier_complete(unsigned* bar, unsigned x, unsigned& nloc, unsigned& nx) {
;     const unsigned G = gridDim.x * gridDim.y * gridDim.z;
;     unsigned sum, cnt, mine, sp = 0u;
;     for (;;) {
;         sum = 0u; cnt = 0u; mine = 0u;
; #pragma unroll
;         for (unsigned j = 0; j < 16; ++j) { const unsigned c = xb_ld(&bar[XB_XCNT(j)]); sum += c; cnt += (c > 0u) ? 1u : 0u; mine = (j == x) ? c : mine; }
; __device__ __forceinline__ void xcd_barrier(const XcdBarrier& b) {
;     asm volatile("s_waitcnt vmcnt(0)" ::: "memory");
;     __syncthreads();
;     if (threadIdx.x == 0) {
;         unsigned* bar = b.bar;
;         __builtin_amdgcn_s_waitcnt(0);
;         unsigned nloc = b.st[0], nx = b.st[1];
;         if (nloc == 0u) { xcd_barrier_complete(bar, b.x, nloc, nx); b.st[0] = nloc; b.st[1] = nx; }
; __global__ void __launch_bounds__(NWAVES * 64, 2) fwd_megakernel(Args args) {
;     ...
;     xcd_barrier(xbar);
.LBB0_638:
	s_setprio 0
	s_barrier
	s_waitcnt vmcnt(0)
	s_barrier
	s_mov_b64 s[0:1], exec
	v_readlane_b32 s4, v254, 3
	v_readlane_b32 s5, v254, 4
	s_and_b64 s[4:5], s[0:1], s[4:5]
	s_mov_b64 exec, s[4:5]
	s_cbranch_execz .LBB0_691
	s_add_i32 s4, 0, 0x23ff0
	v_mov_b32_e32 v0, s4
	s_waitcnt vmcnt(0) expcnt(0) lgkmcnt(0)
	ds_read_b32 v2, v0
	s_add_i32 s4, 0, 0x23ff4
	v_mov_b32_e32 v0, s4
	ds_read_b32 v0, v0
	s_waitcnt lgkmcnt(1)
	v_cmp_ne_u32_e32 vcc, 0, v2
	s_cbranch_vccnz .LBB0_655
	v_readlane_b32 s4, v254, 0
	s_mul_i32 s28, s31, s4
	s_add_u32 s4, s62, 0xc0200
	s_addc_u32 s5, s63, 0
	s_add_u32 s6, s62, 0xc0400
	s_addc_u32 s7, s63, 0
	s_add_u32 s8, s62, 0xc0500
	s_addc_u32 s9, s63, 0
	s_add_u32 s10, s62, 0xc0600
	s_addc_u32 s11, s63, 0
	s_add_u32 s12, s62, 0xc0700
	s_addc_u32 s13, s63, 0
	s_add_u32 s14, s62, 0xc0800
	s_addc_u32 s15, s63, 0
	s_add_u32 s16, s62, 0xc0900
	s_addc_u32 s17, s63, 0
	s_add_u32 s18, s62, 0xc0a00
	s_addc_u32 s19, s63, 0
	s_add_u32 s20, s62, 0xc0b00
	s_addc_u32 s21, s63, 0
	s_add_u32 s22, s62, 0xc0c00
	s_addc_u32 s23, s63, 0
	s_add_u32 s24, s62, 0xc0d00
	s_addc_u32 s25, s63, 0
	s_add_u32 s36, s62, 0xc0e00
	s_addc_u32 s37, s63, 0
	s_add_u32 s38, s62, 0xc0f00
	s_addc_u32 s39, s63, 0
	s_add_u32 s40, s62, 0xc1000
	s_addc_u32 s41, s63, 0
	s_add_u32 s42, s62, 0xc1100
	s_addc_u32 s43, s63, 0
	s_add_u32 s44, s62, 0xc1200
	s_addc_u32 s45, s63, 0
	s_add_u32 s72, s62, 0xc1300
	s_mul_i32 s28, s28, s30
	s_addc_u32 s73, s63, 0
	s_mov_b32 s29, 1
	v_mov_b32_e32 v16, 0
	s_branch .LBB0_643
